# adds QKV q-tile 16B stores (perm32 w_q rows) on top of RESID 16B epilogues, attention batching/LDS-transposed stores, barrier reorder
# speedup vs baseline: 1.0128x; 1.0093x over previous
.LBB0_63:
	s_or_b64 exec, exec, s[2:3]
	s_waitcnt lgkmcnt(0)
	s_barrier
	ds_read_b32 v2, v37
	s_mov_b64 s[2:3], -1
	s_waitcnt lgkmcnt(0)
	v_cmp_lt_i32_e32 vcc, s9, v2
	v_readfirstlane_b32 s29, v2
	s_cbranch_vccnz .LBB0_58
	s_cmpk_gt_u32 s29, 0x67f
	s_cselect_b32 s34, 1, 0
	s_sub_u32 s35, s29, 0x980
	s_cmpk_lt_u32 s35, 32
	s_cselect_b32 s35, 0, 1
	s_and_b32 s34, s34, s35
	s_cmpk_gt_i32 s29, 0xff
	s_mov_b64 s[26:27], -1
	s_cbranch_scc0 .LBB0_83
	s_mov_b64 s[22:23], -1
	s_cmpk_gt_u32 s29, 0x67f
	s_cbranch_scc0 .LBB0_80
	s_cmpk_gt_u32 s29, 0x93f
	s_cbranch_scc0 .LBB0_77
	s_cmpk_gt_u32 s29, 0x97f
	s_cbranch_scc0 .LBB0_74
	s_cmpk_gt_u32 s29, 0x99f
	s_cbranch_scc0 .LBB0_104
	s_cmpk_gt_u32 s29, 0x9df
	s_mov_b64 s[2:3], -1
	s_cbranch_scc0 .LBB0_105
	s_add_i32 s2, s29, 0xfffff620
	s_lshr_b32 s18, s2, 6
	v_readlane_b32 s36, v253, 0
	s_and_b32 s28, s2, 63
	s_lshl_b64 s[2:3], s[18:19], 22
	v_readlane_b32 s40, v253, 4
	v_readlane_b32 s41, v253, 5
	s_add_u32 s12, s40, s2
	v_readlane_b32 s37, v253, 1
	v_readlane_b32 s38, v253, 2
	v_readlane_b32 s39, v253, 3
	v_readlane_b32 s42, v253, 6
	v_readlane_b32 s43, v253, 7
	s_addc_u32 s13, s41, s3
	s_lshl_b64 s[2:3], s[18:19], 21
	v_readlane_b32 s15, v254, 3
	v_readlane_b32 s36, v253, 16
	s_add_u32 s20, s15, s2
	v_readlane_b32 s2, v254, 4
	v_readlane_b32 s37, v253, 17
	v_readlane_b32 s38, v253, 18
	v_readlane_b32 s39, v253, 19
	v_readlane_b32 s40, v253, 20
	v_readlane_b32 s41, v253, 21
	v_readlane_b32 s42, v253, 22
	v_readlane_b32 s43, v253, 23
	v_readlane_b32 s44, v253, 24
	v_readlane_b32 s45, v253, 25
	v_readlane_b32 s46, v253, 26
	v_readlane_b32 s47, v253, 27
	v_readlane_b32 s48, v253, 28
	v_readlane_b32 s49, v253, 29
	v_readlane_b32 s50, v253, 30
	v_readlane_b32 s51, v253, 31
	s_addc_u32 s21, s2, s3
	s_mov_b64 s[24:25], 0
	s_mov_b64 s[2:3], 0
	s_cbranch_execz .LBB0_106

.LBB0_834:
	v_mov_b32_e32 v112, v180
	v_mov_b32_e32 v143, v180
	v_ashrrev_i32_e32 v145, 2, v112
	v_and_b32_e32 v145, 0xffffffc0, v145
	v_lshl_add_u32 v145, s96, 8, v145
	s_lshl_b32 s5, s4, 8
	v_lshrrev_b32_e32 v112, 1, v112
	v_and_or_b32 v174, v143, 15, v145
	v_lshrrev_b32_e32 v143, 2, v143
	s_cmp_gt_i32 s4, 3
	v_ashrrev_i32_e32 v175, 31, v174
	v_and_b32_e32 v112, 0x60, v112
	v_and_b32_e32 v143, 12, v143
	s_cselect_b64 s[12:13], -1, 0
	v_lshlrev_b64 v[178:179], 11, v[174:175]
	v_readlane_b32 s68, v252, 17
	v_or3_b32 v172, v112, v143, s5
	v_lshl_add_u64 v[176:177], s[78:79], 0, v[178:179]
	s_waitcnt vmcnt(0)
	s_and_b64 vcc, exec, s[12:13]
	s_cbranch_vccz .Lmy_q1_epi
	v_pk_mul_f32 v[128:129], v[170:171], v[128:129] op_sel_hi:[0,1]
	v_pk_mul_f32 v[126:127], v[170:171], v[126:127] op_sel_hi:[0,1]
	s_mov_b64 s[4:5], -1
	s_and_b64 vcc, exec, s[12:13]
	v_readlane_b32 s69, v252, 18
	s_cbranch_vccz .LBB0_836
	v_mov_b32_e32 v173, v113
	v_lshl_add_u64 v[148:149], v[172:173], 2, v[176:177]
	v_add_co_u32_e32 v148, vcc, 0xc8a0000, v148
	s_mov_b64 s[4:5], 0
	s_nop 0
	v_addc_co_u32_e32 v149, vcc, 0, v149, vcc
	global_store_dwordx4 v[148:149], v[126:129], off offset:1024

.Lmy_q1_epi:
	v_readlane_b32 s69, v252, 18
	v_add_u32_e32 v194, v172, v143
	v_lshlrev_b32_e32 v196, 11, v174
	v_lshl_add_u32 v196, v194, 1, v196
	v_add_u32_e32 v197, 0x8000, v196
	v_add_u32_e32 v198, 0x10000, v196
	v_add_u32_e32 v199, 0x18000, v196
	v_add_u32_e32 v200, 0x40000, v196
	v_add_u32_e32 v201, 0x48000, v196
	v_add_u32_e32 v202, 0x50000, v196
	v_add_u32_e32 v203, 0x58000, v196
	v_mul_f32_e32 v126, v170, v126
	v_mul_f32_e32 v127, v170, v127
	v_mul_f32_e32 v128, v170, v128
	v_mul_f32_e32 v129, v170, v129
	v_mul_f32_e32 v122, v170, v122
	v_mul_f32_e32 v123, v170, v123
	v_mul_f32_e32 v124, v170, v124
	v_mul_f32_e32 v125, v170, v125
	v_mul_f32_e32 v118, v170, v118
	v_mul_f32_e32 v119, v170, v119
	v_mul_f32_e32 v120, v170, v120
	v_mul_f32_e32 v121, v170, v121
	v_mul_f32_e32 v114, v170, v114
	v_mul_f32_e32 v115, v170, v115
	v_mul_f32_e32 v116, v170, v116
	v_mul_f32_e32 v117, v170, v117
	v_cvt_pk_bf16_f32 v204, v126, v127
	v_cvt_pk_bf16_f32 v205, v128, v129
	v_cvt_pk_bf16_f32 v206, v122, v123
	v_cvt_pk_bf16_f32 v207, v124, v125
	global_store_dwordx4 v196, v[204:207], s[42:43]
	v_cvt_pk_bf16_f32 v208, v118, v119
	v_cvt_pk_bf16_f32 v209, v120, v121
	v_cvt_pk_bf16_f32 v210, v114, v115
	v_cvt_pk_bf16_f32 v211, v116, v117
	global_store_dwordx4 v196, v[208:211], s[42:43] offset:256
	v_mul_f32_e32 v108, v168, v108
	v_mul_f32_e32 v109, v168, v109
	v_mul_f32_e32 v110, v168, v110
	v_mul_f32_e32 v111, v168, v111
	v_mul_f32_e32 v104, v168, v104
	v_mul_f32_e32 v105, v168, v105
	v_mul_f32_e32 v106, v168, v106
	v_mul_f32_e32 v107, v168, v107
	v_mul_f32_e32 v100, v168, v100
	v_mul_f32_e32 v101, v168, v101
	v_mul_f32_e32 v102, v168, v102
	v_mul_f32_e32 v103, v168, v103
	v_mul_f32_e32 v96, v168, v96
	v_mul_f32_e32 v97, v168, v97
	v_mul_f32_e32 v98, v168, v98
	v_mul_f32_e32 v99, v168, v99
	v_cvt_pk_bf16_f32 v212, v108, v109
	v_cvt_pk_bf16_f32 v213, v110, v111
	v_cvt_pk_bf16_f32 v214, v104, v105
	v_cvt_pk_bf16_f32 v215, v106, v107
	global_store_dwordx4 v197, v[212:215], s[42:43]
	v_cvt_pk_bf16_f32 v216, v100, v101
	v_cvt_pk_bf16_f32 v217, v102, v103
	v_cvt_pk_bf16_f32 v218, v96, v97
	v_cvt_pk_bf16_f32 v219, v98, v99
	global_store_dwordx4 v197, v[216:219], s[42:43] offset:256
	v_mul_f32_e32 v92, v166, v92
	v_mul_f32_e32 v93, v166, v93
	v_mul_f32_e32 v94, v166, v94
	v_mul_f32_e32 v95, v166, v95
	v_mul_f32_e32 v88, v166, v88
	v_mul_f32_e32 v89, v166, v89
	v_mul_f32_e32 v90, v166, v90
	v_mul_f32_e32 v91, v166, v91
	v_mul_f32_e32 v84, v166, v84
	v_mul_f32_e32 v85, v166, v85
	v_mul_f32_e32 v86, v166, v86
	v_mul_f32_e32 v87, v166, v87
	v_mul_f32_e32 v80, v166, v80
	v_mul_f32_e32 v81, v166, v81
	v_mul_f32_e32 v82, v166, v82
	v_mul_f32_e32 v83, v166, v83
	v_cvt_pk_bf16_f32 v204, v92, v93
	v_cvt_pk_bf16_f32 v205, v94, v95
	v_cvt_pk_bf16_f32 v206, v88, v89
	v_cvt_pk_bf16_f32 v207, v90, v91
	global_store_dwordx4 v198, v[204:207], s[42:43]
	v_cvt_pk_bf16_f32 v208, v84, v85
	v_cvt_pk_bf16_f32 v209, v86, v87
	v_cvt_pk_bf16_f32 v210, v80, v81
	v_cvt_pk_bf16_f32 v211, v82, v83
	global_store_dwordx4 v198, v[208:211], s[42:43] offset:256
	v_mul_f32_e32 v76, v164, v76
	v_mul_f32_e32 v77, v164, v77
	v_mul_f32_e32 v78, v164, v78
	v_mul_f32_e32 v79, v164, v79
	v_mul_f32_e32 v72, v164, v72
	v_mul_f32_e32 v73, v164, v73
	v_mul_f32_e32 v74, v164, v74
	v_mul_f32_e32 v75, v164, v75
	v_mul_f32_e32 v68, v164, v68
	v_mul_f32_e32 v69, v164, v69
	v_mul_f32_e32 v70, v164, v70
	v_mul_f32_e32 v71, v164, v71
	v_mul_f32_e32 v64, v164, v64
	v_mul_f32_e32 v65, v164, v65
	v_mul_f32_e32 v66, v164, v66
	v_mul_f32_e32 v67, v164, v67
	v_cvt_pk_bf16_f32 v212, v76, v77
	v_cvt_pk_bf16_f32 v213, v78, v79
	v_cvt_pk_bf16_f32 v214, v72, v73
	v_cvt_pk_bf16_f32 v215, v74, v75
	global_store_dwordx4 v199, v[212:215], s[42:43]
	v_cvt_pk_bf16_f32 v216, v68, v69
	v_cvt_pk_bf16_f32 v217, v70, v71
	v_cvt_pk_bf16_f32 v218, v64, v65
	v_cvt_pk_bf16_f32 v219, v66, v67
	global_store_dwordx4 v199, v[216:219], s[42:43] offset:256
	v_mul_f32_e32 v60, v144, v60
	v_mul_f32_e32 v61, v144, v61
	v_mul_f32_e32 v62, v144, v62
	v_mul_f32_e32 v63, v144, v63
	v_mul_f32_e32 v56, v144, v56
	v_mul_f32_e32 v57, v144, v57
	v_mul_f32_e32 v58, v144, v58
	v_mul_f32_e32 v59, v144, v59
	v_mul_f32_e32 v52, v144, v52
	v_mul_f32_e32 v53, v144, v53
	v_mul_f32_e32 v54, v144, v54
	v_mul_f32_e32 v55, v144, v55
	v_mul_f32_e32 v48, v144, v48
	v_mul_f32_e32 v49, v144, v49
	v_mul_f32_e32 v50, v144, v50
	v_mul_f32_e32 v51, v144, v51
	v_cvt_pk_bf16_f32 v204, v60, v61
	v_cvt_pk_bf16_f32 v205, v62, v63
	v_cvt_pk_bf16_f32 v206, v56, v57
	v_cvt_pk_bf16_f32 v207, v58, v59
	global_store_dwordx4 v200, v[204:207], s[42:43]
	v_cvt_pk_bf16_f32 v208, v52, v53
	v_cvt_pk_bf16_f32 v209, v54, v55
	v_cvt_pk_bf16_f32 v210, v48, v49
	v_cvt_pk_bf16_f32 v211, v50, v51
	global_store_dwordx4 v200, v[208:211], s[42:43] offset:256
	v_mul_f32_e32 v44, v142, v44
	v_mul_f32_e32 v45, v142, v45
	v_mul_f32_e32 v46, v142, v46
	v_mul_f32_e32 v47, v142, v47
	v_mul_f32_e32 v40, v142, v40
	v_mul_f32_e32 v41, v142, v41
	v_mul_f32_e32 v42, v142, v42
	v_mul_f32_e32 v43, v142, v43
	v_mul_f32_e32 v36, v142, v36
	v_mul_f32_e32 v37, v142, v37
	v_mul_f32_e32 v38, v142, v38
	v_mul_f32_e32 v39, v142, v39
	v_mul_f32_e32 v32, v142, v32
	v_mul_f32_e32 v33, v142, v33
	v_mul_f32_e32 v34, v142, v34
	v_mul_f32_e32 v35, v142, v35
	v_cvt_pk_bf16_f32 v212, v44, v45
	v_cvt_pk_bf16_f32 v213, v46, v47
	v_cvt_pk_bf16_f32 v214, v40, v41
	v_cvt_pk_bf16_f32 v215, v42, v43
	global_store_dwordx4 v201, v[212:215], s[42:43]
	v_cvt_pk_bf16_f32 v216, v36, v37
	v_cvt_pk_bf16_f32 v217, v38, v39
	v_cvt_pk_bf16_f32 v218, v32, v33
	v_cvt_pk_bf16_f32 v219, v34, v35
	global_store_dwordx4 v201, v[216:219], s[42:43] offset:256
	v_mul_f32_e32 v28, v136, v28
	v_mul_f32_e32 v29, v136, v29
	v_mul_f32_e32 v30, v136, v30
	v_mul_f32_e32 v31, v136, v31
	v_mul_f32_e32 v24, v136, v24
	v_mul_f32_e32 v25, v136, v25
	v_mul_f32_e32 v26, v136, v26
	v_mul_f32_e32 v27, v136, v27
	v_mul_f32_e32 v20, v136, v20
	v_mul_f32_e32 v21, v136, v21
	v_mul_f32_e32 v22, v136, v22
	v_mul_f32_e32 v23, v136, v23
	v_mul_f32_e32 v16, v136, v16
	v_mul_f32_e32 v17, v136, v17
	v_mul_f32_e32 v18, v136, v18
	v_mul_f32_e32 v19, v136, v19
	v_cvt_pk_bf16_f32 v204, v28, v29
	v_cvt_pk_bf16_f32 v205, v30, v31
	v_cvt_pk_bf16_f32 v206, v24, v25
	v_cvt_pk_bf16_f32 v207, v26, v27
	global_store_dwordx4 v202, v[204:207], s[42:43]
	v_cvt_pk_bf16_f32 v208, v20, v21
	v_cvt_pk_bf16_f32 v209, v22, v23
	v_cvt_pk_bf16_f32 v210, v16, v17
	v_cvt_pk_bf16_f32 v211, v18, v19
	global_store_dwordx4 v202, v[208:211], s[42:43] offset:256
	v_mul_f32_e32 v12, v137, v12
	v_mul_f32_e32 v13, v137, v13
	v_mul_f32_e32 v14, v137, v14
	v_mul_f32_e32 v15, v137, v15
	v_mul_f32_e32 v8, v137, v8
	v_mul_f32_e32 v9, v137, v9
	v_mul_f32_e32 v10, v137, v10
	v_mul_f32_e32 v11, v137, v11
	v_mul_f32_e32 v4, v137, v4
	v_mul_f32_e32 v5, v137, v5
	v_mul_f32_e32 v6, v137, v6
	v_mul_f32_e32 v7, v137, v7
	v_mul_f32_e32 v0, v137, v0
	v_mul_f32_e32 v1, v137, v1
	v_mul_f32_e32 v2, v137, v2
	v_mul_f32_e32 v3, v137, v3
	v_cvt_pk_bf16_f32 v212, v12, v13
	v_cvt_pk_bf16_f32 v213, v14, v15
	v_cvt_pk_bf16_f32 v214, v8, v9
	v_cvt_pk_bf16_f32 v215, v10, v11
	global_store_dwordx4 v203, v[212:215], s[42:43]
	v_cvt_pk_bf16_f32 v216, v4, v5
	v_cvt_pk_bf16_f32 v217, v6, v7
	v_cvt_pk_bf16_f32 v218, v0, v1
	v_cvt_pk_bf16_f32 v219, v2, v3
	global_store_dwordx4 v203, v[216:219], s[42:43] offset:256
	s_branch .LBB0_962
